# sparse/own: removed the 56 explicit lgkmcnt(0) waits around wave-private LDS stages (same-wave LDS ops execute in order); on top of v75
# baseline (speedup 1.0000x reference)
.LBB0_822:
	s_or_b64 exec, exec, s[30:31]
.LBB0_823:
	s_mov_b64 s[8:9], 0
	s_andn2_b64 vcc, exec, s[6:7]
	s_mov_b32 s68, s38
	s_mov_b32 s38, s12
	v_mov_b32_e32 v207, v206
	s_mov_b32 s66, s67
	s_cbranch_vccz .LBB0_860

.LBB0_831:
	s_waitcnt vmcnt(0)
	ds_write_b128 v201, v[92:95]
	ds_write_b128 v201, v[108:111] offset:1280
	ds_read_b128 v[112:115], v202
	ds_read_b128 v[116:119], v202 offset:32
	ds_write_b128 v201, v[104:107]
	ds_write_b128 v201, v[88:91] offset:1280
	ds_read_b128 v[120:123], v202
	ds_read_b128 v[124:127], v202 offset:32
	ds_write_b128 v201, v[84:87]
	ds_write_b128 v201, v[100:103] offset:1280
	ds_read_b128 v[128:131], v202
	ds_read_b128 v[132:135], v202 offset:32
	ds_write_b128 v201, v[96:99]
	ds_write_b128 v201, v[80:83] offset:1280
	ds_read_b128 v[136:139], v202
	ds_read_b128 v[140:143], v202 offset:32
	s_add_i32 s67, s66, 1
	v_cmp_ge_u32_e64 s[6:7], s67, v186
	s_and_b64 vcc, exec, s[6:7]
	s_cbranch_vccnz .LBB0_833
	ds_bpermute_b32 v0, v188, v206
	ds_bpermute_b32 v4, v189, v206
	s_ashr_i32 s8, s38, 8
	s_ashr_i32 s9, s8, 31
	s_lshl_b64 s[8:9], s[8:9], 13
	s_waitcnt lgkmcnt(1)
	v_lshrrev_b32_e32 v1, 2, v0
	v_cmp_ne_u32_e32 vcc, -1, v0
	s_waitcnt lgkmcnt(0)
	v_lshrrev_b32_e32 v5, 2, v4
	s_lshl_b32 s12, s38, 3
	v_cndmask_b32_e32 v176, 0, v1, vcc
	v_cmp_ne_u32_e32 vcc, -1, v4
	v_lshl_add_u64 v[0:1], s[8:9], 0, v[176:177]
	v_lshlrev_b64 v[0:1], 11, v[0:1]
	v_cndmask_b32_e32 v176, 0, v5, vcc
	v_lshl_add_u64 v[4:5], s[8:9], 0, v[176:177]
	v_lshl_add_u64 v[0:1], s[34:35], 0, v[0:1]
	s_and_b32 s12, s12, 0x700
	v_lshlrev_b64 v[4:5], 11, v[4:5]
	v_lshl_add_u64 v[0:1], v[0:1], 0, s[12:13]
	v_mov_b32_e32 v185, v177
	v_lshl_add_u64 v[4:5], s[34:35], 0, v[4:5]
	v_lshl_add_u64 v[0:1], v[0:1], 0, v[184:185]
	v_lshl_add_u64 v[4:5], v[4:5], 0, s[12:13]
	v_lshl_add_u64 v[4:5], v[4:5], 0, v[184:185]
	global_load_dwordx4 v[92:95], v[0:1], off
	global_load_dwordx4 v[104:107], v[0:1], off offset:64
	global_load_dwordx4 v[108:111], v[4:5], off
	global_load_dwordx4 v[88:91], v[4:5], off offset:64
	global_load_dwordx4 v[84:87], v[0:1], off offset:128
	global_load_dwordx4 v[96:99], v[0:1], off offset:192
	global_load_dwordx4 v[100:103], v[4:5], off offset:128
	global_load_dwordx4 v[80:83], v[4:5], off offset:192

.LBB0_844:
	s_or_b64 exec, exec, s[8:9]
	v_cvt_pk_bf16_f32 v48, v48, v49
	v_cvt_pk_bf16_f32 v49, v50, v51
	ds_write_b64 v204, v[48:49]
	v_cvt_pk_bf16_f32 v48, v52, v53
	v_cvt_pk_bf16_f32 v49, v54, v55
	v_cndmask_b32_e32 v64, -1, v64, vcc
	ds_write_b64 v204, v[48:49] offset:16
	v_cvt_pk_bf16_f32 v48, v56, v57
	v_cvt_pk_bf16_f32 v49, v58, v59
	ds_bpermute_b32 v176, v188, v64
	ds_write_b64 v204, v[48:49] offset:32
	v_cvt_pk_bf16_f32 v48, v60, v61
	v_cvt_pk_bf16_f32 v49, v62, v63
	ds_write_b64 v204, v[48:49] offset:48
	ds_bpermute_b32 v64, v189, v64
	ds_read_b128 v[48:51], v205
	s_waitcnt lgkmcnt(4)
	v_lshlrev_b64 v[52:53], 8, v[176:177]
	v_cmp_lt_i32_e32 vcc, -1, v176
	v_lshl_add_u64 v[52:53], v[182:183], 0, v[52:53]
	v_add_u32_e32 v56, v179, v178
	s_and_saveexec_b64 s[8:9], vcc
	s_cbranch_execz .LBB0_846
	ds_read_b128 v[58:61], v56
	s_waitcnt lgkmcnt(0)
	global_store_dwordx4 v[52:53], v[58:61], off
	s_add_u32 s98, s98, 1

.LBB0_848:
	s_or_b64 exec, exec, s[30:31]
	v_cvt_pk_bf16_f32 v32, v32, v33
	v_cvt_pk_bf16_f32 v33, v34, v35
	ds_write_b64 v204, v[32:33]
	v_cvt_pk_bf16_f32 v32, v36, v37
	v_cvt_pk_bf16_f32 v33, v38, v39
	ds_write_b64 v204, v[32:33] offset:16
	v_cvt_pk_bf16_f32 v32, v40, v41
	v_cvt_pk_bf16_f32 v33, v42, v43
	ds_write_b64 v204, v[32:33] offset:32
	v_cvt_pk_bf16_f32 v32, v44, v45
	v_cvt_pk_bf16_f32 v33, v46, v47
	ds_write_b64 v204, v[32:33] offset:48
	ds_read_b128 v[32:35], v205
	s_and_saveexec_b64 s[30:31], vcc
	s_cbranch_execz .LBB0_850
	ds_read_b128 v[36:39], v56
	s_waitcnt lgkmcnt(0)
	global_store_dwordx4 v[52:53], v[36:39], off offset:64
	s_add_u32 s98, s98, 1

.LBB0_852:
	s_or_b64 exec, exec, s[30:31]
	v_cvt_pk_bf16_f32 v16, v16, v17
	v_cvt_pk_bf16_f32 v17, v18, v19
	ds_write_b64 v204, v[16:17]
	v_cvt_pk_bf16_f32 v16, v20, v21
	v_cvt_pk_bf16_f32 v17, v22, v23
	ds_write_b64 v204, v[16:17] offset:16
	v_cvt_pk_bf16_f32 v16, v24, v25
	v_cvt_pk_bf16_f32 v17, v26, v27
	ds_write_b64 v204, v[16:17] offset:32
	v_cvt_pk_bf16_f32 v16, v28, v29
	v_cvt_pk_bf16_f32 v17, v30, v31
	ds_write_b64 v204, v[16:17] offset:48
	ds_read_b128 v[16:19], v205
	s_and_saveexec_b64 s[30:31], vcc
	s_cbranch_execz .LBB0_854
	ds_read_b128 v[20:23], v56
	s_waitcnt lgkmcnt(0)
	global_store_dwordx4 v[52:53], v[20:23], off offset:128
	s_add_u32 s98, s98, 1

.LBB0_856:
	s_or_b64 exec, exec, s[30:31]
	v_cvt_pk_bf16_f32 v0, v0, v1
	v_cvt_pk_bf16_f32 v1, v2, v3
	ds_write_b64 v204, v[0:1]
	v_cvt_pk_bf16_f32 v0, v4, v5
	v_cvt_pk_bf16_f32 v1, v6, v7
	ds_write_b64 v204, v[0:1] offset:16
	v_cvt_pk_bf16_f32 v0, v8, v9
	v_cvt_pk_bf16_f32 v1, v10, v11
	ds_write_b64 v204, v[0:1] offset:32
	v_cvt_pk_bf16_f32 v0, v12, v13
	v_cvt_pk_bf16_f32 v1, v14, v15
	ds_write_b64 v204, v[0:1] offset:48
	ds_read_b128 v[0:3], v205
	s_and_saveexec_b64 s[30:31], vcc
	s_cbranch_execz .LBB0_858
	ds_read_b128 v[4:7], v56
	s_waitcnt lgkmcnt(0)
	global_store_dwordx4 v[52:53], v[4:7], off offset:192
	s_add_u32 s98, s98, 1

.LBB0_925:
	s_waitcnt vmcnt(2)
	v_cndmask_b32_e32 v64, 0, v129, vcc
	v_cndmask_b32_e64 v65, v128, 0, s[86:87]
	v_cndmask_b32_e64 v66, 0, v130, s[38:39]
	v_add_f32_e32 v64, v65, v64
	v_add_f32_e32 v64, v66, v64
	s_waitcnt lgkmcnt(0)
	v_add_f32_e32 v65, v159, v161
	v_add_f32_e32 v64, v64, v65
	v_div_scale_f32 v65, s[38:39], v64, v64, 1.0
	v_rcp_f32_e32 v66, v65
	s_add_u32 s38, s58, s96
	s_addc_u32 s39, s59, 0
	s_add_i32 s86, s62, 1
	v_fma_f32 v67, -v65, v66, 1.0
	v_fmac_f32_e32 v66, v67, v66
	v_div_scale_f32 v67, vcc, 1.0, v64, 1.0
	s_waitcnt vmcnt(0)
	v_mul_f32_e32 v68, v67, v66
	v_fma_f32 v69, -v65, v68, v67
	v_fmac_f32_e32 v68, v69, v66
	v_fma_f32 v65, -v65, v68, v67
	v_div_fmas_f32 v65, v65, v66, v68
	v_div_fixup_f32 v68, v65, v64, 1.0
	v_mul_f32_e32 v48, v68, v48
	v_mul_f32_e32 v49, v68, v49
	v_cvt_pk_bf16_f32 v48, v48, v49
	v_mul_f32_e32 v49, v68, v50
	v_mul_f32_e32 v50, v68, v51
	v_cvt_pk_bf16_f32 v49, v49, v50
	ds_write_b64 v158, v[48:49]
	v_mul_f32_e32 v48, v68, v52
	v_mul_f32_e32 v49, v68, v53
	v_cvt_pk_bf16_f32 v48, v48, v49
	v_mul_f32_e32 v49, v68, v54
	v_mul_f32_e32 v50, v68, v55
	v_cvt_pk_bf16_f32 v49, v49, v50
	ds_write_b64 v158, v[48:49] offset:16
	v_mul_f32_e32 v48, v68, v56
	v_mul_f32_e32 v49, v68, v57
	v_cvt_pk_bf16_f32 v48, v48, v49
	v_mul_f32_e32 v49, v68, v58
	v_mul_f32_e32 v50, v68, v59
	v_cvt_pk_bf16_f32 v49, v49, v50
	ds_write_b64 v158, v[48:49] offset:32
	v_mul_f32_e32 v48, v68, v60
	v_mul_f32_e32 v49, v68, v61
	v_cvt_pk_bf16_f32 v48, v48, v49
	v_mul_f32_e32 v49, v68, v62
	v_mul_f32_e32 v50, v68, v63
	v_cvt_pk_bf16_f32 v49, v49, v50
	ds_write_b64 v158, v[48:49] offset:48
	ds_read_b128 v[48:51], v157
	ds_read_b128 v[52:55], v160
	v_mov_b32_e32 v65, s39
	v_or_b32_e32 v64, s38, v132
	v_lshlrev_b64 v[64:65], 11, v[64:65]
	v_mov_b32_e32 v67, s39
	v_or_b32_e32 v66, s38, v134
	v_lshlrev_b64 v[56:57], 11, v[66:67]
	v_lshl_add_u64 v[58:59], v[142:143], 0, v[64:65]
	v_lshl_add_u64 v[56:57], v[142:143], 0, v[56:57]
	s_waitcnt lgkmcnt(0)
	global_store_dwordx4 v[58:59], v[52:55], off
	global_store_dwordx4 v[56:57], v[48:51], off
	v_mul_f32_e32 v32, v68, v32
	v_mul_f32_e32 v33, v68, v33
	v_cvt_pk_bf16_f32 v32, v32, v33
	v_mul_f32_e32 v33, v68, v34
	v_mul_f32_e32 v34, v68, v35
	v_cvt_pk_bf16_f32 v33, v33, v34
	ds_write_b64 v158, v[32:33]
	v_mul_f32_e32 v32, v68, v36
	v_mul_f32_e32 v33, v68, v37
	v_cvt_pk_bf16_f32 v32, v32, v33
	v_mul_f32_e32 v33, v68, v38
	v_mul_f32_e32 v34, v68, v39
	v_cvt_pk_bf16_f32 v33, v33, v34
	ds_write_b64 v158, v[32:33] offset:16
	v_mul_f32_e32 v32, v68, v40
	v_mul_f32_e32 v33, v68, v41
	v_cvt_pk_bf16_f32 v32, v32, v33
	v_mul_f32_e32 v33, v68, v42
	v_mul_f32_e32 v34, v68, v43
	v_cvt_pk_bf16_f32 v33, v33, v34
	ds_write_b64 v158, v[32:33] offset:32
	v_mul_f32_e32 v32, v68, v44
	v_mul_f32_e32 v33, v68, v45
	v_cvt_pk_bf16_f32 v32, v32, v33
	v_mul_f32_e32 v33, v68, v46
	v_mul_f32_e32 v34, v68, v47
	v_cvt_pk_bf16_f32 v33, v33, v34
	ds_write_b64 v158, v[32:33] offset:48
	ds_read_b128 v[32:35], v160
	ds_read_b128 v[36:39], v157
	s_waitcnt lgkmcnt(1)
	global_store_dwordx4 v[58:59], v[32:35], off offset:64
	s_waitcnt lgkmcnt(0)
	global_store_dwordx4 v[56:57], v[36:39], off offset:64
	v_mul_f32_e32 v16, v68, v16
	v_mul_f32_e32 v17, v68, v17
	v_cvt_pk_bf16_f32 v16, v16, v17
	v_mul_f32_e32 v17, v68, v18
	v_mul_f32_e32 v18, v68, v19
	v_cvt_pk_bf16_f32 v17, v17, v18
	ds_write_b64 v158, v[16:17]
	v_mul_f32_e32 v16, v68, v20
	v_mul_f32_e32 v17, v68, v21
	v_cvt_pk_bf16_f32 v16, v16, v17
	v_mul_f32_e32 v17, v68, v22
	v_mul_f32_e32 v18, v68, v23
	v_cvt_pk_bf16_f32 v17, v17, v18
	ds_write_b64 v158, v[16:17] offset:16
	v_mul_f32_e32 v16, v68, v24
	v_mul_f32_e32 v17, v68, v25
	v_cvt_pk_bf16_f32 v16, v16, v17
	v_mul_f32_e32 v17, v68, v26
	v_mul_f32_e32 v18, v68, v27
	v_cvt_pk_bf16_f32 v17, v17, v18
	ds_write_b64 v158, v[16:17] offset:32
	v_mul_f32_e32 v16, v68, v28
	v_mul_f32_e32 v17, v68, v29
	v_cvt_pk_bf16_f32 v16, v16, v17
	v_mul_f32_e32 v17, v68, v30
	v_mul_f32_e32 v18, v68, v31
	v_cvt_pk_bf16_f32 v17, v17, v18
	ds_write_b64 v158, v[16:17] offset:48
	ds_read_b128 v[16:19], v160
	ds_read_b128 v[20:23], v157
	s_waitcnt lgkmcnt(1)
	global_store_dwordx4 v[58:59], v[16:19], off offset:128
	s_waitcnt lgkmcnt(0)
	global_store_dwordx4 v[56:57], v[20:23], off offset:128
	v_mul_f32_e32 v0, v68, v0
	v_mul_f32_e32 v1, v68, v1
	v_cvt_pk_bf16_f32 v0, v0, v1
	v_mul_f32_e32 v1, v68, v2
	v_mul_f32_e32 v2, v68, v3
	v_cvt_pk_bf16_f32 v1, v1, v2
	ds_write_b64 v158, v[0:1]
	v_mul_f32_e32 v0, v68, v4
	v_mul_f32_e32 v1, v68, v5
	v_cvt_pk_bf16_f32 v0, v0, v1
	v_mul_f32_e32 v1, v68, v6
	v_mul_f32_e32 v2, v68, v7
	v_cvt_pk_bf16_f32 v1, v1, v2
	ds_write_b64 v158, v[0:1] offset:16
	v_mul_f32_e32 v0, v68, v8
	v_mul_f32_e32 v1, v68, v9
	v_cvt_pk_bf16_f32 v0, v0, v1
	v_mul_f32_e32 v1, v68, v10
	v_mul_f32_e32 v2, v68, v11
	v_cvt_pk_bf16_f32 v1, v1, v2
	ds_write_b64 v158, v[0:1] offset:32
	v_mul_f32_e32 v0, v68, v12
	v_mul_f32_e32 v1, v68, v13
	v_cvt_pk_bf16_f32 v0, v0, v1
	v_mul_f32_e32 v1, v68, v14
	v_mul_f32_e32 v2, v68, v15
	v_cvt_pk_bf16_f32 v1, v1, v2
	ds_write_b64 v158, v[0:1] offset:48
	ds_read_b128 v[0:3], v160
	ds_read_b128 v[4:7], v157
	s_cmp_lg_u32 s62, 3
	s_cselect_b32 s38, s86, 3
	s_add_i32 s62, s38, s44
	s_ashr_i32 s38, s62, 8
	s_lshl_b32 s87, s62, 8
	s_ashr_i32 s39, s38, 31
	s_and_b32 s87, s87, 0x1f00
	s_waitcnt lgkmcnt(1)
	global_store_dwordx4 v[58:59], v[0:3], off offset:192
	s_waitcnt lgkmcnt(0)
	global_store_dwordx4 v[56:57], v[4:7], off offset:192
	s_lshl_b64 s[38:39], s[38:39], 13
	s_add_i32 s87, s87, s64
	v_mbcnt_lo_u32_b32 v2, -1, 0
	v_mbcnt_hi_u32_b32 v2, -1, v2
	s_add_u32 s38, s38, s87
	v_ashrrev_i32_e32 v0, 2, v2
	v_ashrrev_i32_e32 v1, 31, v0
	s_addc_u32 s39, s39, 0
	v_lshl_add_u64 v[0:1], s[38:39], 0, v[0:1]
	v_lshlrev_b64 v[0:1], 11, v[0:1]
	s_lshl_b32 s38, s62, 3
	v_lshl_add_u64 v[0:1], s[56:57], 0, v[0:1]
	s_and_b32 s62, s38, 0x700
	v_lshlrev_b32_e32 v2, 4, v2
	v_lshl_add_u64 v[0:1], v[0:1], 0, s[62:63]
	v_and_b32_e32 v138, 48, v2
	v_lshl_add_u64 v[16:17], v[0:1], 0, v[138:139]
	v_add_co_u32_e32 v24, vcc, 0x8000, v16
	s_cmp_lg_u32 s86, 4
	s_nop 0
	v_addc_co_u32_e32 v25, vcc, 0, v17, vcc
	global_load_dwordx4 v[0:3], v[16:17], off
	global_load_dwordx4 v[4:7], v[16:17], off offset:64
	global_load_dwordx4 v[20:23], v[24:25], off
	global_load_dwordx4 v[12:15], v[24:25], off offset:64
	global_load_dwordx4 v[8:11], v[16:17], off offset:128
	s_nop 0
	global_load_dwordx4 v[16:19], v[16:17], off offset:192
	s_nop 0
	global_load_dwordx4 v[28:31], v[24:25], off offset:128
	s_nop 0
	global_load_dwordx4 v[24:27], v[24:25], off offset:192
	s_mov_b32 s62, s86
	s_cbranch_scc0 .LBB0_938

.LBB0_928:
	s_add_i32 s96, s96, s64
	v_or_b32_e32 v138, s96, v131
	v_lshl_add_u64 v[32:33], s[84:85], 0, v[138:139]
	v_mad_u64_u32 v[34:35], s[38:39], v32, 12, s[60:61]
	v_mad_i32_i24 v35, v33, 12, v35
	global_load_dwordx3 v[128:130], v[34:35], off
	s_waitcnt vmcnt(0)
	s_waitcnt vmcnt(0) lgkmcnt(0)
	s_barrier
	ds_write_b128 v155, v[0:3]
	ds_write_b128 v155, v[20:23] offset:1280
	ds_read_b128 v[80:83], v156
	ds_read_b128 v[84:87], v156 offset:32
	ds_write_b128 v155, v[4:7]
	ds_write_b128 v155, v[12:15] offset:1280
	ds_read_b128 v[88:91], v156
	ds_read_b128 v[92:95], v156 offset:32
	ds_write_b128 v155, v[8:11]
	ds_write_b128 v155, v[28:31] offset:1280
	ds_read_b128 v[96:99], v156
	ds_read_b128 v[100:103], v156 offset:32
	ds_write_b128 v155, v[16:19]
	ds_write_b128 v155, v[24:27] offset:1280
	ds_read_b128 v[104:107], v156
	ds_read_b128 v[108:111], v156 offset:32
	v_mov_b32_e32 v159, 0
	v_mov_b32_e32 v112, v154
	v_mov_b32_e32 v113, v153
	v_mov_b32_e32 v114, v152
	v_mov_b32_e32 v115, v151
	v_mov_b32_e32 v116, v150
	v_mov_b32_e32 v117, v149
	v_mov_b32_e32 v118, v148
	v_mov_b32_e32 v119, v147
	v_mov_b32_e32 v120, v146
	s_mov_b32 s38, s94
	v_mov_b32_e32 v0, 0
	v_mov_b32_e32 v1, v159
	v_mov_b32_e32 v2, v159
	v_mov_b32_e32 v3, v159
	v_mov_b32_e32 v4, v159
	v_mov_b32_e32 v5, v159
	v_mov_b32_e32 v6, v159
	v_mov_b32_e32 v7, v159
	v_mov_b32_e32 v8, v159
	v_mov_b32_e32 v9, v159
	v_mov_b32_e32 v10, v159
	v_mov_b32_e32 v11, v159
	v_mov_b32_e32 v12, v159
	v_mov_b32_e32 v13, v159
	v_mov_b32_e32 v14, v159
	v_mov_b32_e32 v15, v159
	v_mov_b32_e32 v16, 0
	v_mov_b32_e32 v17, v159
	v_mov_b32_e32 v18, v159
	v_mov_b32_e32 v19, v159
	v_mov_b32_e32 v20, v159
	v_mov_b32_e32 v21, v159
	v_mov_b32_e32 v22, v159
	v_mov_b32_e32 v23, v159
	v_mov_b32_e32 v24, v159
	v_mov_b32_e32 v25, v159
	v_mov_b32_e32 v26, v159
	v_mov_b32_e32 v27, v159
	v_mov_b32_e32 v28, v159
	v_mov_b32_e32 v29, v159
	v_mov_b32_e32 v30, v159
	v_mov_b32_e32 v31, v159
	v_mov_b32_e32 v32, 0
	v_mov_b32_e32 v33, v159
	v_mov_b32_e32 v34, v159
	v_mov_b32_e32 v35, v159
	v_mov_b32_e32 v36, v159
	v_mov_b32_e32 v37, v159
	v_mov_b32_e32 v38, v159
	v_mov_b32_e32 v39, v159
	v_mov_b32_e32 v40, v159
	v_mov_b32_e32 v41, v159
	v_mov_b32_e32 v42, v159
	v_mov_b32_e32 v43, v159
	v_mov_b32_e32 v44, v159
	v_mov_b32_e32 v45, v159
	v_mov_b32_e32 v46, v159
	v_mov_b32_e32 v47, v159
	v_mov_b32_e32 v48, 0
	v_mov_b32_e32 v49, v159
	v_mov_b32_e32 v50, v159
	v_mov_b32_e32 v51, v159
	v_mov_b32_e32 v52, v159
	v_mov_b32_e32 v53, v159
	v_mov_b32_e32 v54, v159
	v_mov_b32_e32 v55, v159
	v_mov_b32_e32 v56, v159
	v_mov_b32_e32 v57, v159
	v_mov_b32_e32 v58, v159
	v_mov_b32_e32 v59, v159
	v_mov_b32_e32 v60, v159
	v_mov_b32_e32 v61, v159
	v_mov_b32_e32 v62, v159
	v_mov_b32_e32 v63, v159
	s_branch .LBB0_930

.LBB0_935:
	v_add_u32_e32 v138, 48, v144
	v_mov_b32_e32 v145, v139
	v_lshlrev_b64 v[162:163], 8, v[138:139]
	v_lshlrev_b64 v[144:145], 8, v[144:145]
	v_lshl_add_u64 v[186:187], v[140:141], 0, v[162:163]
	v_lshl_add_u64 v[144:145], v[140:141], 0, v[144:145]
	global_load_dwordx4 v[162:165], v[144:145], off
	global_load_dwordx4 v[166:169], v[186:187], off
	global_load_dwordx4 v[170:173], v[144:145], off offset:64
	global_load_dwordx4 v[174:177], v[186:187], off offset:64
	global_load_dwordx4 v[178:181], v[144:145], off offset:128
	global_load_dwordx4 v[182:185], v[186:187], off offset:128
	s_nop 0
	global_load_dwordx4 v[186:189], v[186:187], off offset:192
	s_nop 0
	global_load_dwordx4 v[190:193], v[144:145], off offset:192
	s_waitcnt vmcnt(7)
	ds_write_b128 v160, v[162:165]
	s_waitcnt vmcnt(6)
	ds_write_b128 v157, v[166:169]
	ds_read2_b64 v[162:165], v158 offset1:2
	ds_read2_b64 v[166:169], v158 offset0:4 offset1:6
	s_waitcnt vmcnt(5)
	ds_write_b128 v160, v[170:173]
	s_waitcnt vmcnt(4)
	ds_write_b128 v157, v[174:177]
	ds_read2_b64 v[170:173], v158 offset1:2
	ds_read2_b64 v[174:177], v158 offset0:4 offset1:6
	s_waitcnt vmcnt(3)
	ds_write_b128 v160, v[178:181]
	s_waitcnt vmcnt(2)
	ds_write_b128 v157, v[182:185]
	ds_read2_b64 v[178:181], v158 offset1:2
	s_waitcnt lgkmcnt(8)
	v_lshlrev_b32_e32 v138, 16, v162
	v_add_f32_e32 v48, v48, v138
	s_waitcnt lgkmcnt(4)
	v_lshlrev_b32_e32 v138, 16, v170
	v_add_f32_e32 v32, v32, v138
	s_waitcnt lgkmcnt(0)
	v_lshlrev_b32_e32 v138, 16, v178
	v_and_b32_e32 v144, 0xffff0000, v162
	v_lshlrev_b32_e32 v145, 16, v163
	v_and_b32_e32 v162, 0xffff0000, v163
	v_lshlrev_b32_e32 v163, 16, v164
	v_and_b32_e32 v164, 0xffff0000, v164
	v_lshlrev_b32_e32 v182, 16, v165
	v_and_b32_e32 v165, 0xffff0000, v165
	v_add_f32_e32 v16, v16, v138
	v_and_b32_e32 v138, 0xffff0000, v178
	v_add_f32_e32 v51, v51, v162
	v_add_f32_e32 v52, v52, v163
	v_add_f32_e32 v53, v53, v164
	v_add_f32_e32 v55, v55, v165
	v_and_b32_e32 v162, 0xffff0000, v171
	v_lshlrev_b32_e32 v163, 16, v172
	v_and_b32_e32 v164, 0xffff0000, v172
	v_lshlrev_b32_e32 v165, 16, v173
	v_add_f32_e32 v17, v17, v138
	v_lshlrev_b32_e32 v138, 16, v179
	v_add_f32_e32 v35, v35, v162
	v_add_f32_e32 v36, v36, v163
	v_add_f32_e32 v37, v37, v164
	v_add_f32_e32 v38, v38, v165
	ds_read2_b64 v[162:165], v158 offset0:4 offset1:6
	v_add_f32_e32 v18, v18, v138
	v_and_b32_e32 v138, 0xffff0000, v179
	v_add_f32_e32 v19, v19, v138
	v_lshlrev_b32_e32 v138, 16, v180
	v_add_f32_e32 v20, v20, v138
	v_and_b32_e32 v138, 0xffff0000, v180
	v_add_f32_e32 v21, v21, v138
	v_lshlrev_b32_e32 v138, 16, v181
	v_add_f32_e32 v22, v22, v138
	v_and_b32_e32 v138, 0xffff0000, v181
	v_add_f32_e32 v23, v23, v138
	s_waitcnt lgkmcnt(0)
	v_lshlrev_b32_e32 v138, 16, v162
	v_lshlrev_b32_e32 v183, 16, v166
	v_and_b32_e32 v166, 0xffff0000, v166
	v_lshlrev_b32_e32 v184, 16, v167
	v_and_b32_e32 v167, 0xffff0000, v167
	v_lshlrev_b32_e32 v185, 16, v168
	v_and_b32_e32 v168, 0xffff0000, v168
	v_lshlrev_b32_e32 v194, 16, v169
	v_and_b32_e32 v169, 0xffff0000, v169
	v_add_f32_e32 v24, v24, v138
	v_and_b32_e32 v138, 0xffff0000, v162
	s_waitcnt vmcnt(0)
	ds_write_b128 v160, v[190:193]
	ds_write_b128 v157, v[186:189]
	v_add_f32_e32 v57, v57, v166
	v_add_f32_e32 v59, v59, v167
	v_add_f32_e32 v61, v61, v168
	v_add_f32_e32 v63, v63, v169
	v_and_b32_e32 v166, 0xffff0000, v173
	v_lshlrev_b32_e32 v167, 16, v174
	v_and_b32_e32 v168, 0xffff0000, v174
	v_lshlrev_b32_e32 v169, 16, v175
	v_add_f32_e32 v25, v25, v138
	v_lshlrev_b32_e32 v138, 16, v163
	v_add_f32_e32 v39, v39, v166
	v_add_f32_e32 v40, v40, v167
	v_add_f32_e32 v41, v41, v168
	v_add_f32_e32 v42, v42, v169
	v_add_f32_e32 v26, v26, v138
	v_and_b32_e32 v138, 0xffff0000, v163
	ds_read2_b64 v[166:169], v158 offset1:2
	v_add_f32_e32 v27, v27, v138
	v_lshlrev_b32_e32 v138, 16, v164
	v_add_f32_e32 v28, v28, v138
	v_and_b32_e32 v138, 0xffff0000, v164
	v_add_f32_e32 v29, v29, v138
	v_lshlrev_b32_e32 v138, 16, v165
	v_add_f32_e32 v30, v30, v138
	v_and_b32_e32 v138, 0xffff0000, v165
	v_add_f32_e32 v31, v31, v138
	s_waitcnt lgkmcnt(0)
	v_lshlrev_b32_e32 v138, 16, v166
	v_add_f32_e32 v0, v0, v138
	v_and_b32_e32 v138, 0xffff0000, v166
	v_add_f32_e32 v1, v1, v138
	v_lshlrev_b32_e32 v138, 16, v167
	ds_read2_b64 v[162:165], v158 offset0:4 offset1:6
	v_add_f32_e32 v2, v2, v138
	v_and_b32_e32 v138, 0xffff0000, v167
	v_add_f32_e32 v3, v3, v138
	v_lshlrev_b32_e32 v138, 16, v168
	v_add_f32_e32 v4, v4, v138
	v_and_b32_e32 v138, 0xffff0000, v168
	v_add_f32_e32 v5, v5, v138
	v_lshlrev_b32_e32 v138, 16, v169
	v_add_f32_e32 v6, v6, v138
	v_and_b32_e32 v138, 0xffff0000, v169
	v_add_f32_e32 v7, v7, v138
	s_waitcnt lgkmcnt(0)
	v_lshlrev_b32_e32 v138, 16, v162
	v_add_f32_e32 v8, v8, v138
	v_and_b32_e32 v138, 0xffff0000, v162
	v_add_f32_e32 v9, v9, v138
	v_lshlrev_b32_e32 v138, 16, v163
	v_add_f32_e32 v10, v10, v138
	v_and_b32_e32 v138, 0xffff0000, v163
	v_add_f32_e32 v11, v11, v138
	v_lshlrev_b32_e32 v138, 16, v164
	v_add_f32_e32 v12, v12, v138
	v_and_b32_e32 v138, 0xffff0000, v164
	v_add_f32_e32 v13, v13, v138
	v_lshlrev_b32_e32 v138, 16, v165
	v_add_f32_e32 v49, v49, v144
	v_add_f32_e32 v50, v50, v145
	v_and_b32_e32 v144, 0xffff0000, v170
	v_lshlrev_b32_e32 v145, 16, v171
	v_and_b32_e32 v170, 0xffff0000, v175
	v_lshlrev_b32_e32 v171, 16, v176
	v_and_b32_e32 v172, 0xffff0000, v176
	v_lshlrev_b32_e32 v173, 16, v177
	v_and_b32_e32 v174, 0xffff0000, v177
	v_add_f32_e32 v14, v14, v138
	v_and_b32_e32 v138, 0xffff0000, v165
	v_add_f32_e32 v54, v54, v182
	v_add_f32_e32 v56, v56, v183
	v_add_f32_e32 v58, v58, v184
	v_add_f32_e32 v60, v60, v185
	v_add_f32_e32 v62, v62, v194
	v_add_f32_e32 v33, v33, v144
	v_add_f32_e32 v34, v34, v145
	v_add_f32_e32 v43, v43, v170
	v_add_f32_e32 v44, v44, v171
	v_add_f32_e32 v45, v45, v172
	v_add_f32_e32 v46, v46, v173
	v_add_f32_e32 v47, v47, v174
	v_add_f32_e32 v15, v15, v138
	s_cmp_gt_u32 s97, 1
	s_cselect_b64 vcc, -1, 0
	s_cmp_lt_u32 s97, 2
	s_cbranch_scc1 .LBB0_934
.LBB0_936:
	s_waitcnt vmcnt(15)
	ds_write_b128 v160, v[120:123]
	s_waitcnt vmcnt(13)
	ds_write_b128 v157, v[124:127]
	ds_read2_b64 v[120:123], v158 offset1:2
	ds_read2_b64 v[124:127], v158 offset0:4 offset1:6
	ds_write_b128 v160, v[112:115]
	s_waitcnt vmcnt(12)
	ds_write_b128 v157, v[116:119]
	s_waitcnt lgkmcnt(3)
	v_lshlrev_b32_e32 v138, 16, v120
	v_and_b32_e32 v120, 0xffff0000, v120
	v_add_f32_e32 v49, v49, v120
	v_lshlrev_b32_e32 v120, 16, v121
	v_add_f32_e32 v50, v50, v120
	v_and_b32_e32 v120, 0xffff0000, v121
	v_add_f32_e32 v51, v51, v120
	v_lshlrev_b32_e32 v120, 16, v122
	v_add_f32_e32 v52, v52, v120
	v_and_b32_e32 v120, 0xffff0000, v122
	v_add_f32_e32 v53, v53, v120
	v_lshlrev_b32_e32 v120, 16, v123
	v_add_f32_e32 v54, v54, v120
	v_and_b32_e32 v120, 0xffff0000, v123
	v_add_f32_e32 v55, v55, v120
	s_waitcnt lgkmcnt(2)
	v_lshlrev_b32_e32 v120, 16, v124
	v_add_f32_e32 v56, v56, v120
	v_and_b32_e32 v120, 0xffff0000, v124
	v_add_f32_e32 v57, v57, v120
	v_lshlrev_b32_e32 v120, 16, v125
	v_add_f32_e32 v58, v58, v120
	v_and_b32_e32 v120, 0xffff0000, v125
	v_add_f32_e32 v59, v59, v120
	v_lshlrev_b32_e32 v120, 16, v126
	ds_read2_b64 v[112:115], v158 offset1:2
	ds_read2_b64 v[116:119], v158 offset0:4 offset1:6
	v_add_f32_e32 v60, v60, v120
	v_and_b32_e32 v120, 0xffff0000, v126
	v_add_f32_e32 v61, v61, v120
	v_lshlrev_b32_e32 v120, 16, v127
	v_add_f32_e32 v62, v62, v120
	v_and_b32_e32 v120, 0xffff0000, v127
	v_add_f32_e32 v63, v63, v120
	s_waitcnt lgkmcnt(1)
	v_lshlrev_b32_e32 v120, 16, v112
	v_and_b32_e32 v112, 0xffff0000, v112
	v_add_f32_e32 v33, v33, v112
	v_lshlrev_b32_e32 v112, 16, v113
	v_add_f32_e32 v34, v34, v112
	v_and_b32_e32 v112, 0xffff0000, v113
	v_add_f32_e32 v35, v35, v112
	v_lshlrev_b32_e32 v112, 16, v114
	v_add_f32_e32 v36, v36, v112
	v_and_b32_e32 v112, 0xffff0000, v114
	v_add_f32_e32 v37, v37, v112
	v_lshlrev_b32_e32 v112, 16, v115
	v_add_f32_e32 v38, v38, v112
	v_and_b32_e32 v112, 0xffff0000, v115
	v_add_f32_e32 v39, v39, v112
	s_waitcnt lgkmcnt(0)
	v_lshlrev_b32_e32 v112, 16, v116
	v_add_f32_e32 v40, v40, v112
	v_and_b32_e32 v112, 0xffff0000, v116
	v_add_f32_e32 v41, v41, v112
	v_lshlrev_b32_e32 v112, 16, v117
	s_waitcnt vmcnt(11)
	ds_write_b128 v160, v[104:107]
	s_waitcnt vmcnt(9)
	ds_write_b128 v157, v[108:111]
	v_add_f32_e32 v42, v42, v112
	v_and_b32_e32 v112, 0xffff0000, v117
	v_add_f32_e32 v43, v43, v112
	v_lshlrev_b32_e32 v112, 16, v118
	ds_read2_b64 v[104:107], v158 offset1:2
	ds_read2_b64 v[108:111], v158 offset0:4 offset1:6
	v_add_f32_e32 v44, v44, v112
	v_and_b32_e32 v112, 0xffff0000, v118
	v_add_f32_e32 v45, v45, v112
	v_lshlrev_b32_e32 v112, 16, v119
	v_add_f32_e32 v46, v46, v112
	v_and_b32_e32 v112, 0xffff0000, v119
	v_add_f32_e32 v47, v47, v112
	s_waitcnt lgkmcnt(1)
	v_lshlrev_b32_e32 v112, 16, v104
	v_and_b32_e32 v104, 0xffff0000, v104
	v_add_f32_e32 v17, v17, v104
	v_lshlrev_b32_e32 v104, 16, v105
	v_add_f32_e32 v18, v18, v104
	v_and_b32_e32 v104, 0xffff0000, v105
	v_add_f32_e32 v19, v19, v104
	v_lshlrev_b32_e32 v104, 16, v106
	v_add_f32_e32 v20, v20, v104
	v_and_b32_e32 v104, 0xffff0000, v106
	v_add_f32_e32 v21, v21, v104
	v_lshlrev_b32_e32 v104, 16, v107
	v_add_f32_e32 v22, v22, v104
	v_and_b32_e32 v104, 0xffff0000, v107
	v_add_f32_e32 v23, v23, v104
	s_waitcnt lgkmcnt(0)
	v_lshlrev_b32_e32 v104, 16, v108
	v_add_f32_e32 v24, v24, v104
	v_and_b32_e32 v104, 0xffff0000, v108
	v_add_f32_e32 v25, v25, v104
	v_lshlrev_b32_e32 v104, 16, v109
	ds_write_b128 v160, v[96:99]
	s_waitcnt vmcnt(8)
	ds_write_b128 v157, v[100:103]
	v_add_f32_e32 v26, v26, v104
	v_and_b32_e32 v104, 0xffff0000, v109
	v_add_f32_e32 v27, v27, v104
	v_lshlrev_b32_e32 v104, 16, v110
	ds_read2_b64 v[96:99], v158 offset1:2
	ds_read2_b64 v[100:103], v158 offset0:4 offset1:6
	v_add_f32_e32 v28, v28, v104
	v_and_b32_e32 v104, 0xffff0000, v110
	v_add_f32_e32 v29, v29, v104
	v_lshlrev_b32_e32 v104, 16, v111
	v_add_f32_e32 v30, v30, v104
	v_and_b32_e32 v104, 0xffff0000, v111
	v_add_f32_e32 v31, v31, v104
	s_waitcnt lgkmcnt(1)
	v_lshlrev_b32_e32 v104, 16, v96
	v_and_b32_e32 v96, 0xffff0000, v96
	v_add_f32_e32 v1, v1, v96
	v_lshlrev_b32_e32 v96, 16, v97
	v_add_f32_e32 v2, v2, v96
	v_and_b32_e32 v96, 0xffff0000, v97
	v_add_f32_e32 v3, v3, v96
	v_lshlrev_b32_e32 v96, 16, v98
	v_add_f32_e32 v4, v4, v96
	v_and_b32_e32 v96, 0xffff0000, v98
	v_add_f32_e32 v5, v5, v96
	v_lshlrev_b32_e32 v96, 16, v99
	v_add_f32_e32 v6, v6, v96
	v_and_b32_e32 v96, 0xffff0000, v99
	v_add_f32_e32 v7, v7, v96
	s_waitcnt lgkmcnt(0)
	v_lshlrev_b32_e32 v96, 16, v100
	v_add_f32_e32 v8, v8, v96
	v_and_b32_e32 v96, 0xffff0000, v100
	v_add_f32_e32 v9, v9, v96
	v_lshlrev_b32_e32 v96, 16, v101
	v_add_f32_e32 v10, v10, v96
	v_and_b32_e32 v96, 0xffff0000, v101
	v_add_f32_e32 v11, v11, v96
	v_lshlrev_b32_e32 v96, 16, v102
	v_add_f32_e32 v12, v12, v96
	v_and_b32_e32 v96, 0xffff0000, v102
	v_add_f32_e32 v13, v13, v96
	v_lshlrev_b32_e32 v96, 16, v103
	v_add_f32_e32 v14, v14, v96
	v_and_b32_e32 v96, 0xffff0000, v103
	v_add_f32_e32 v48, v48, v138
	v_add_f32_e32 v32, v32, v120
	v_add_f32_e32 v16, v16, v112
	v_add_f32_e32 v0, v0, v104
	v_add_f32_e32 v15, v15, v96
	s_cmp_gt_u32 s97, 2
	s_cselect_b64 s[38:39], -1, 0
	s_cmp_lt_u32 s97, 3
	s_cbranch_scc1 .LBB0_925
.LBB0_937:
	s_waitcnt vmcnt(7)
	ds_write_b128 v160, v[88:91]
	s_waitcnt vmcnt(5)
	ds_write_b128 v157, v[92:95]
	ds_read2_b64 v[88:91], v158 offset1:2
	ds_read2_b64 v[92:95], v158 offset0:4 offset1:6
	ds_write_b128 v160, v[80:83]
	s_waitcnt vmcnt(4)
	ds_write_b128 v157, v[84:87]
	s_waitcnt lgkmcnt(3)
	v_lshlrev_b32_e32 v96, 16, v88
	v_and_b32_e32 v88, 0xffff0000, v88
	v_add_f32_e32 v49, v49, v88
	v_lshlrev_b32_e32 v88, 16, v89
	v_add_f32_e32 v50, v50, v88
	v_and_b32_e32 v88, 0xffff0000, v89
	v_add_f32_e32 v51, v51, v88
	v_lshlrev_b32_e32 v88, 16, v90
	v_add_f32_e32 v52, v52, v88
	v_and_b32_e32 v88, 0xffff0000, v90
	v_add_f32_e32 v53, v53, v88
	v_lshlrev_b32_e32 v88, 16, v91
	v_add_f32_e32 v54, v54, v88
	v_and_b32_e32 v88, 0xffff0000, v91
	v_add_f32_e32 v55, v55, v88
	s_waitcnt lgkmcnt(2)
	v_lshlrev_b32_e32 v88, 16, v92
	v_add_f32_e32 v56, v56, v88
	v_and_b32_e32 v88, 0xffff0000, v92
	v_add_f32_e32 v57, v57, v88
	v_lshlrev_b32_e32 v88, 16, v93
	v_add_f32_e32 v58, v58, v88
	v_and_b32_e32 v88, 0xffff0000, v93
	v_add_f32_e32 v59, v59, v88
	v_lshlrev_b32_e32 v88, 16, v94
	ds_read2_b64 v[80:83], v158 offset1:2
	ds_read2_b64 v[84:87], v158 offset0:4 offset1:6
	v_add_f32_e32 v60, v60, v88
	v_and_b32_e32 v88, 0xffff0000, v94
	v_add_f32_e32 v61, v61, v88
	v_lshlrev_b32_e32 v88, 16, v95
	v_add_f32_e32 v62, v62, v88
	v_and_b32_e32 v88, 0xffff0000, v95
	v_add_f32_e32 v63, v63, v88
	s_waitcnt lgkmcnt(1)
	v_lshlrev_b32_e32 v88, 16, v80
	v_and_b32_e32 v80, 0xffff0000, v80
	v_add_f32_e32 v33, v33, v80
	v_lshlrev_b32_e32 v80, 16, v81
	v_add_f32_e32 v34, v34, v80
	v_and_b32_e32 v80, 0xffff0000, v81
	v_add_f32_e32 v35, v35, v80
	v_lshlrev_b32_e32 v80, 16, v82
	v_add_f32_e32 v36, v36, v80
	v_and_b32_e32 v80, 0xffff0000, v82
	v_add_f32_e32 v37, v37, v80
	v_lshlrev_b32_e32 v80, 16, v83
	v_add_f32_e32 v38, v38, v80
	v_and_b32_e32 v80, 0xffff0000, v83
	v_add_f32_e32 v39, v39, v80
	s_waitcnt lgkmcnt(0)
	v_lshlrev_b32_e32 v80, 16, v84
	v_add_f32_e32 v40, v40, v80
	v_and_b32_e32 v80, 0xffff0000, v84
	v_add_f32_e32 v41, v41, v80
	v_lshlrev_b32_e32 v80, 16, v85
	s_waitcnt vmcnt(3)
	ds_write_b128 v160, v[72:75]
	s_waitcnt vmcnt(1)
	ds_write_b128 v157, v[76:79]
	v_add_f32_e32 v42, v42, v80
	v_and_b32_e32 v80, 0xffff0000, v85
	v_add_f32_e32 v43, v43, v80
	v_lshlrev_b32_e32 v80, 16, v86
	ds_read2_b64 v[72:75], v158 offset1:2
	ds_read2_b64 v[76:79], v158 offset0:4 offset1:6
	v_add_f32_e32 v44, v44, v80
	v_and_b32_e32 v80, 0xffff0000, v86
	v_add_f32_e32 v45, v45, v80
	v_lshlrev_b32_e32 v80, 16, v87
	v_add_f32_e32 v46, v46, v80
	v_and_b32_e32 v80, 0xffff0000, v87
	v_add_f32_e32 v47, v47, v80
	s_waitcnt lgkmcnt(1)
	v_lshlrev_b32_e32 v80, 16, v72
	v_and_b32_e32 v72, 0xffff0000, v72
	v_add_f32_e32 v17, v17, v72
	v_lshlrev_b32_e32 v72, 16, v73
	v_add_f32_e32 v18, v18, v72
	v_and_b32_e32 v72, 0xffff0000, v73
	v_add_f32_e32 v19, v19, v72
	v_lshlrev_b32_e32 v72, 16, v74
	v_add_f32_e32 v20, v20, v72
	v_and_b32_e32 v72, 0xffff0000, v74
	v_add_f32_e32 v21, v21, v72
	v_lshlrev_b32_e32 v72, 16, v75
	v_add_f32_e32 v22, v22, v72
	v_and_b32_e32 v72, 0xffff0000, v75
	v_add_f32_e32 v23, v23, v72
	s_waitcnt lgkmcnt(0)
	v_lshlrev_b32_e32 v72, 16, v76
	v_add_f32_e32 v24, v24, v72
	v_and_b32_e32 v72, 0xffff0000, v76
	v_add_f32_e32 v25, v25, v72
	v_lshlrev_b32_e32 v72, 16, v77
	ds_write_b128 v160, v[64:67]
	s_waitcnt vmcnt(0)
	ds_write_b128 v157, v[68:71]
	v_add_f32_e32 v26, v26, v72
	v_and_b32_e32 v72, 0xffff0000, v77
	v_add_f32_e32 v27, v27, v72
	v_lshlrev_b32_e32 v72, 16, v78
	ds_read2_b64 v[64:67], v158 offset1:2
	ds_read2_b64 v[68:71], v158 offset0:4 offset1:6
	v_add_f32_e32 v28, v28, v72
	v_and_b32_e32 v72, 0xffff0000, v78
	v_add_f32_e32 v29, v29, v72
	v_lshlrev_b32_e32 v72, 16, v79
	v_add_f32_e32 v30, v30, v72
	v_and_b32_e32 v72, 0xffff0000, v79
	v_add_f32_e32 v31, v31, v72
	s_waitcnt lgkmcnt(1)
	v_lshlrev_b32_e32 v72, 16, v64
	v_and_b32_e32 v64, 0xffff0000, v64
	v_add_f32_e32 v1, v1, v64
	v_lshlrev_b32_e32 v64, 16, v65
	v_add_f32_e32 v2, v2, v64
	v_and_b32_e32 v64, 0xffff0000, v65
	v_add_f32_e32 v3, v3, v64
	v_lshlrev_b32_e32 v64, 16, v66
	v_add_f32_e32 v4, v4, v64
	v_and_b32_e32 v64, 0xffff0000, v66
	v_add_f32_e32 v5, v5, v64
	v_lshlrev_b32_e32 v64, 16, v67
	v_add_f32_e32 v6, v6, v64
	v_and_b32_e32 v64, 0xffff0000, v67
	v_add_f32_e32 v7, v7, v64
	s_waitcnt lgkmcnt(0)
	v_lshlrev_b32_e32 v64, 16, v68
	v_add_f32_e32 v8, v8, v64
	v_and_b32_e32 v64, 0xffff0000, v68
	v_add_f32_e32 v9, v9, v64
	v_lshlrev_b32_e32 v64, 16, v69
	v_add_f32_e32 v10, v10, v64
	v_and_b32_e32 v64, 0xffff0000, v69
	v_add_f32_e32 v11, v11, v64
	v_lshlrev_b32_e32 v64, 16, v70
	v_add_f32_e32 v12, v12, v64
	v_and_b32_e32 v64, 0xffff0000, v70
	v_add_f32_e32 v13, v13, v64
	v_lshlrev_b32_e32 v64, 16, v71
	v_add_f32_e32 v14, v14, v64
	v_and_b32_e32 v64, 0xffff0000, v71
	v_add_f32_e32 v48, v48, v96
	v_add_f32_e32 v32, v32, v88
	v_add_f32_e32 v16, v16, v80
	v_add_f32_e32 v0, v0, v72
	v_add_f32_e32 v15, v15, v64
	s_branch .LBB0_925
